# attention loop: K-fragment LDS reads issued before the next-tile global loads at each tile start
# baseline (speedup 1.0000x reference)
.Lq1_body:
	ds_read_b128 v[44:47], v214 offset:35840
	ds_read_b128 v[72:75], v214 offset:35904
	ds_read_b128 v[92:95], v214 offset:40192
	ds_read_b128 v[112:115], v214 offset:40256
	ds_read_b128 v[132:135], v214 offset:44544
	ds_read_b128 v[148:151], v214 offset:44608
	ds_read_b128 v[136:139], v214 offset:48896
	ds_read_b128 v[152:155], v214 offset:48960
	global_load_dwordx4 v[28:31], v202, s[100:101] offset:-128
	global_load_dwordx4 v[32:35], v202, s[100:101]
	global_load_dwordx4 v[4:7], v203, s[100:101] offset:-128
	global_load_dwordx4 v[12:15], v203, s[100:101]
	s_waitcnt lgkmcnt(7)
	v_mfma_f32_16x16x32_bf16 v[140:143], v[44:47], v[8:11], 0
	v_mfma_f32_16x16x32_bf16 v[44:47], v[44:47], v[20:23], 0
	s_waitcnt lgkmcnt(1)
	v_mfma_f32_16x16x32_bf16 v[156:159], v[92:95], v[8:11], 0
	v_mfma_f32_16x16x32_bf16 v[92:95], v[92:95], v[20:23], 0
	v_mfma_f32_16x16x32_bf16 v[160:163], v[132:135], v[8:11], 0
	v_mfma_f32_16x16x32_bf16 v[132:135], v[132:135], v[20:23], 0
	v_mfma_f32_16x16x32_bf16 v[164:167], v[136:139], v[8:11], 0
	v_mfma_f32_16x16x32_bf16 v[168:171], v[136:139], v[20:23], 0
	v_mfma_f32_16x16x32_bf16 v[144:147], v[72:75], v[16:19], v[140:143]
	v_mfma_f32_16x16x32_bf16 v[136:139], v[72:75], v[24:27], v[44:47]
	v_mfma_f32_16x16x32_bf16 v[44:47], v[112:115], v[16:19], v[156:159]
	v_mfma_f32_16x16x32_bf16 v[92:95], v[112:115], v[24:27], v[92:95]
	v_mfma_f32_16x16x32_bf16 v[140:143], v[148:151], v[16:19], v[160:163]
	v_mfma_f32_16x16x32_bf16 v[132:135], v[148:151], v[24:27], v[132:135]
	s_waitcnt lgkmcnt(0)
	v_mfma_f32_16x16x32_bf16 v[72:75], v[152:155], v[16:19], v[164:167]
	v_mfma_f32_16x16x32_bf16 v[112:115], v[152:155], v[24:27], v[168:171]
	s_cmp_eq_u32 s98, 0
	s_cbranch_scc1 .LBB0_859
	v_sub_f32_e32 v147, v147, v196
	v_sub_f32_e32 v146, v146, v196
	v_sub_f32_e32 v145, v145, v196
	v_sub_f32_e32 v144, v144, v196
	v_sub_f32_e32 v47, v47, v196
	v_sub_f32_e32 v46, v46, v196
	v_sub_f32_e32 v45, v45, v196
	v_sub_f32_e32 v44, v44, v196
	v_sub_f32_e32 v143, v143, v196
	v_sub_f32_e32 v142, v142, v196
	v_sub_f32_e32 v141, v141, v196
	v_sub_f32_e32 v140, v140, v196
	v_sub_f32_e32 v75, v75, v196
	v_sub_f32_e32 v74, v74, v196
	v_sub_f32_e32 v73, v73, v196
	v_sub_f32_e32 v72, v72, v196
	v_sub_f32_e32 v139, v139, v197
	v_sub_f32_e32 v138, v138, v197
	v_sub_f32_e32 v137, v137, v197
	v_sub_f32_e32 v136, v136, v197
	v_sub_f32_e32 v95, v95, v197
	v_sub_f32_e32 v94, v94, v197
	v_sub_f32_e32 v93, v93, v197
	v_sub_f32_e32 v92, v92, v197
	v_sub_f32_e32 v135, v135, v197
	v_sub_f32_e32 v134, v134, v197
	v_sub_f32_e32 v133, v133, v197
	v_sub_f32_e32 v132, v132, v197
	v_sub_f32_e32 v115, v115, v197
	v_sub_f32_e32 v114, v114, v197
	v_sub_f32_e32 v113, v113, v197
	v_sub_f32_e32 v112, v112, v197

.LBB0_866:
	s_waitcnt lgkmcnt(0)
	s_barrier
	s_cselect_b32 s99, 1, 0
	s_cmp_ge_u32 s89, s83
	s_cbranch_scc1 .Lq1_h2_pvpre
	ds_read_b128 v[36:39], v214
	ds_read_b128 v[40:43], v214 offset:64
	ds_read_b128 v[60:63], v214 offset:4352
	ds_read_b128 v[84:87], v214 offset:4416
	ds_read_b128 v[64:67], v214 offset:8704
	ds_read_b128 v[124:127], v214 offset:8768
	ds_read_b128 v[108:111], v214 offset:13056
	ds_read_b128 v[100:103], v214 offset:13120
	s_cmp_eq_u32 s99, 0
	s_cbranch_scc1 .Lq1_h2_nok
	global_load_dwordx4 v[28:31], v202, s[100:101] offset:-128
	global_load_dwordx4 v[32:35], v202, s[100:101]
.Lq1_h2_nok:
	global_load_dwordx4 v[4:7], v203, s[100:101] offset:-128
	global_load_dwordx4 v[12:15], v203, s[100:101]
	s_waitcnt lgkmcnt(7)
	v_mfma_f32_16x16x32_bf16 v[120:123], v[36:39], v[8:11], 0
	v_mfma_f32_16x16x32_bf16 v[36:39], v[36:39], v[20:23], 0
	s_waitcnt lgkmcnt(1)
	v_mfma_f32_16x16x32_bf16 v[116:119], v[60:63], v[8:11], 0
	v_mfma_f32_16x16x32_bf16 v[60:63], v[60:63], v[20:23], 0
	v_mfma_f32_16x16x32_bf16 v[96:99], v[64:67], v[8:11], 0
	v_mfma_f32_16x16x32_bf16 v[64:67], v[64:67], v[20:23], 0
	v_mfma_f32_16x16x32_bf16 v[104:107], v[108:111], v[8:11], 0
	v_mfma_f32_16x16x32_bf16 v[76:79], v[108:111], v[20:23], 0
	v_mfma_f32_16x16x32_bf16 v[128:131], v[40:43], v[16:19], v[120:123]
	v_mfma_f32_16x16x32_bf16 v[108:111], v[40:43], v[24:27], v[36:39]
	v_mfma_f32_16x16x32_bf16 v[36:39], v[84:87], v[16:19], v[116:119]
	v_mfma_f32_16x16x32_bf16 v[60:63], v[84:87], v[24:27], v[60:63]
	v_mfma_f32_16x16x32_bf16 v[120:123], v[124:127], v[16:19], v[96:99]
	v_mfma_f32_16x16x32_bf16 v[64:67], v[124:127], v[24:27], v[64:67]
	s_waitcnt lgkmcnt(0)
	v_mfma_f32_16x16x32_bf16 v[40:43], v[100:103], v[16:19], v[104:107]
	v_mfma_f32_16x16x32_bf16 v[84:87], v[100:103], v[24:27], v[76:79]
	s_cmp_eq_u32 s98, 0
	s_cbranch_scc1 .LBB0_875
	v_sub_f32_e32 v131, v131, v196
	v_sub_f32_e32 v130, v130, v196
	v_sub_f32_e32 v129, v129, v196
	v_sub_f32_e32 v128, v128, v196
	v_sub_f32_e32 v39, v39, v196
	v_sub_f32_e32 v38, v38, v196
	v_sub_f32_e32 v37, v37, v196
	v_sub_f32_e32 v36, v36, v196
	v_sub_f32_e32 v123, v123, v196
	v_sub_f32_e32 v122, v122, v196
	v_sub_f32_e32 v121, v121, v196
	v_sub_f32_e32 v120, v120, v196
	v_sub_f32_e32 v43, v43, v196
	v_sub_f32_e32 v42, v42, v196
	v_sub_f32_e32 v41, v41, v196
	v_sub_f32_e32 v40, v40, v196
	v_sub_f32_e32 v111, v111, v197
	v_sub_f32_e32 v110, v110, v197
	v_sub_f32_e32 v109, v109, v197
	v_sub_f32_e32 v108, v108, v197
	v_sub_f32_e32 v63, v63, v197
	v_sub_f32_e32 v62, v62, v197
	v_sub_f32_e32 v61, v61, v197
	v_sub_f32_e32 v60, v60, v197
	v_sub_f32_e32 v67, v67, v197
	v_sub_f32_e32 v66, v66, v197
	v_sub_f32_e32 v65, v65, v197
	v_sub_f32_e32 v64, v64, v197
	v_sub_f32_e32 v87, v87, v197
	v_sub_f32_e32 v86, v86, v197
	v_sub_f32_e32 v85, v85, v197
	v_sub_f32_e32 v84, v84, v197

.Lq1_h2_pvpre:
	s_cmp_eq_u32 s99, 0
	s_cbranch_scc1 .Lq1_h2_pvpre2
	global_load_dwordx4 v[28:31], v202, s[100:101] offset:-128
	global_load_dwordx4 v[32:35], v202, s[100:101]
.Lq1_h2_pvpre2:
	global_load_dwordx4 v[4:7], v203, s[100:101] offset:-128
	global_load_dwordx4 v[12:15], v203, s[100:101]
.Lq1_h2_pvonly:
	ds_read_b64_tr_b16 v[64:65], v215 offset:53248
	ds_read_b64_tr_b16 v[108:109], v215 offset:53280
	ds_read_b64_tr_b16 v[120:121], v215 offset:53312
	ds_read_b64_tr_b16 v[128:129], v215 offset:53344
	ds_read_b64_tr_b16 v[66:67], v215 offset:57856
	ds_read_b64_tr_b16 v[110:111], v215 offset:57888
	ds_read_b64_tr_b16 v[122:123], v215 offset:57920
	ds_read_b64_tr_b16 v[130:131], v215 offset:57952
	s_waitcnt lgkmcnt(3)
	v_mfma_f32_16x16x32_bf16 v[124:127], v[44:47], v[64:67], v[144:147]
	v_mfma_f32_16x16x32_bf16 v[64:67], v[92:95], v[64:67], v[140:143]
	s_waitcnt lgkmcnt(2)
	v_mfma_f32_16x16x32_bf16 v[100:103], v[44:47], v[108:111], v[148:151]
	v_mfma_f32_16x16x32_bf16 v[108:111], v[92:95], v[108:111], v[136:139]
	s_waitcnt lgkmcnt(1)
	v_mfma_f32_16x16x32_bf16 v[116:119], v[44:47], v[120:123], v[156:159]
	v_mfma_f32_16x16x32_bf16 v[96:99], v[92:95], v[120:123], v[152:155]
	s_waitcnt lgkmcnt(0)
	v_mfma_f32_16x16x32_bf16 v[104:107], v[44:47], v[128:131], v[164:167]
	v_mfma_f32_16x16x32_bf16 v[76:79], v[92:95], v[128:131], v[160:163]
	ds_read_b64_tr_b16 v[120:121], v215 offset:53376
	ds_read_b64_tr_b16 v[128:129], v215 offset:53408
	ds_read_b64_tr_b16 v[88:89], v215 offset:53440
	ds_read_b64_tr_b16 v[80:81], v215 offset:53472
	ds_read_b64_tr_b16 v[122:123], v215 offset:57984
	ds_read_b64_tr_b16 v[130:131], v215 offset:58016
	ds_read_b64_tr_b16 v[90:91], v215 offset:58048
	ds_read_b64_tr_b16 v[82:83], v215 offset:58080
	s_waitcnt lgkmcnt(3)
	v_mfma_f32_16x16x32_bf16 v[52:55], v[44:47], v[120:123], v[172:175]
	v_mfma_f32_16x16x32_bf16 v[68:71], v[92:95], v[120:123], v[168:171]
	s_waitcnt lgkmcnt(2)
	v_mfma_f32_16x16x32_bf16 v[48:51], v[44:47], v[128:131], v[176:179]
	v_mfma_f32_16x16x32_bf16 v[56:59], v[92:95], v[128:131], v[132:135]
	s_waitcnt lgkmcnt(1)
	v_mfma_f32_16x16x32_bf16 v[218:221], v[44:47], v[88:91], v[184:187]
	v_mfma_f32_16x16x32_bf16 v[222:225], v[92:95], v[88:91], v[180:183]
	s_waitcnt lgkmcnt(0)
	v_mfma_f32_16x16x32_bf16 v[226:229], v[44:47], v[80:83], v[192:195]
	v_mfma_f32_16x16x32_bf16 v[230:233], v[92:95], v[80:83], v[188:191]
	ds_read_b64_tr_b16 v[120:121], v215 offset:62464
	ds_read_b64_tr_b16 v[88:89], v215 offset:62496
	ds_read_b64_tr_b16 v[80:81], v215 offset:62528
	ds_read_b64_tr_b16 v[234:235], v215 offset:62560
	ds_read_b64_tr_b16 v[122:123], v216 offset:13824
	ds_read_b64_tr_b16 v[90:91], v216 offset:13856
	ds_read_b64_tr_b16 v[82:83], v216 offset:13888
	ds_read_b64_tr_b16 v[236:237], v216 offset:13920
	s_waitcnt lgkmcnt(3)
	v_mfma_f32_16x16x32_bf16 v[128:131], v[72:75], v[120:123], v[124:127]
	v_mfma_f32_16x16x32_bf16 v[120:123], v[112:115], v[120:123], v[64:67]
	s_waitcnt lgkmcnt(2)
	v_mfma_f32_16x16x32_bf16 v[124:127], v[72:75], v[88:91], v[100:103]
	v_mfma_f32_16x16x32_bf16 v[108:111], v[112:115], v[88:91], v[108:111]
	s_waitcnt lgkmcnt(1)
	v_mfma_f32_16x16x32_bf16 v[116:119], v[72:75], v[80:83], v[116:119]
	v_mfma_f32_16x16x32_bf16 v[100:103], v[112:115], v[80:83], v[96:99]
	s_waitcnt lgkmcnt(0)
	v_mfma_f32_16x16x32_bf16 v[104:107], v[72:75], v[234:237], v[104:107]
	v_mfma_f32_16x16x32_bf16 v[96:99], v[112:115], v[234:237], v[76:79]
	ds_read_b64_tr_b16 v[64:65], v215 offset:62592
	ds_read_b64_tr_b16 v[234:235], v215 offset:62624
	ds_read_b64_tr_b16 v[238:239], v215 offset:62656
	ds_read_b64_tr_b16 v[242:243], v215 offset:62688
	ds_read_b64_tr_b16 v[66:67], v216 offset:13952
	ds_read_b64_tr_b16 v[236:237], v216 offset:13984
	ds_read_b64_tr_b16 v[240:241], v216 offset:14016
	ds_read_b64_tr_b16 v[244:245], v216 offset:14048
	s_waitcnt lgkmcnt(3)
	v_mfma_f32_16x16x32_bf16 v[88:91], v[72:75], v[64:67], v[52:55]
	v_mfma_f32_16x16x32_bf16 v[76:79], v[112:115], v[64:67], v[68:71]
	s_waitcnt lgkmcnt(2)
	v_mfma_f32_16x16x32_bf16 v[80:83], v[72:75], v[234:237], v[48:51]
	v_mfma_f32_16x16x32_bf16 v[64:67], v[112:115], v[234:237], v[56:59]
	s_waitcnt lgkmcnt(1)
	v_mfma_f32_16x16x32_bf16 v[68:71], v[72:75], v[238:241], v[218:221]
	v_mfma_f32_16x16x32_bf16 v[52:55], v[112:115], v[238:241], v[222:225]
	s_waitcnt lgkmcnt(0)
	v_mfma_f32_16x16x32_bf16 v[56:59], v[72:75], v[242:245], v[226:229]
	v_mfma_f32_16x16x32_bf16 v[48:51], v[112:115], v[242:245], v[230:233]
	s_mov_b64 s[2:3], 0
	s_waitcnt vmcnt(0)
	ds_write_b128 v211, v[28:31] offset:35840
	ds_write_b128 v211, v[32:35] offset:35968
	ds_write_b128 v213, v[4:7] offset:17408
	ds_write_b128 v213, v[12:15] offset:17536
	s_add_u32 s100, s100, 0x4000
	s_addc_u32 s101, s101, 0
	s_addk_i32 s87, 0x80
	s_mov_b32 s89, s88
	s_add_i32 s88, s88, 2
	s_cmp_lt_u32 s88, s84
	s_branch .LBB0_882
